# drop scores-PV grid barrier (same-WG dependency); attention loop: remove redundant s_nop after v_max asm, saddr LDS-DMA
# speedup vs baseline: 1.0093x; 1.0093x over previous
; #define LAS __attribute__((address_space(3)))
; __device__ __forceinline__ void at_tile(LAS unsigned char* Kb, LAS unsigned char* Vb, const LAS float* biasl, int r, int g, int k0, int qw0, int qrow, float cfar,
;                                         const bf16x8 (&qf)[2][2], float (&mrow)[2], f32x4 (&ol)[2], f32x4 (&o)[2][8], bool first) {
;     ...
;     float mx[2];
; #pragma unroll
;     for (int m = 0; m < 2; ++m) {
;         float v = max3f(s[m][0][0], s[m][0][1], s[m][0][2]);
;         v = max3f(v, s[m][0][3], s[m][1][0]); v = max3f(v, s[m][1][1], s[m][1][2]); v = max3f(v, s[m][1][3], s[m][2][0]);
;         v = max3f(v, s[m][2][1], s[m][2][2]); v = max3f(v, s[m][2][3], s[m][3][0]); v = max3f(v, s[m][3][1], s[m][3][2]); v = max2f(v, s[m][3][3]);
;         mx[m] = xl_max(v);
;     }
; #pragma unroll
;     for (int db = 4; db < 8; ++db)
; #pragma unroll
;         for (int kk = 0; kk < 2; ++kk) vf[db * 2 + kk] = *(const LAS bf16x8*)(Vb + (db * 16 + r) * AT_VROW + (((kk * 4 + g) ^ (r >> 1)) * 16));
;     __builtin_amdgcn_sched_barrier(0);
;     if (first || __any(max2f(mx[0], mx[1]) > 10.0f)) {
; #pragma unroll
;         for (int m = 0; m < 2; ++m) {
;             const float delta = first ? mx[m] : fmaxf(mx[m], 0.f), alpha = first ? 0.f : fast_exp2(-delta);
;             mrow[m] = first ? delta : mrow[m] + delta;
;             ol[m] = ol[m] * alpha;
; #pragma unroll
;             for (int db = 0; db < 8; ++db) o[m][db] = o[m][db] * alpha;
; #pragma unroll
;             for (int kb = 0; kb < 4; ++kb) s[m][kb] = s[m][kb] - delta;
;         }
;     }
; #pragma unroll
;     for (int kb = 0; kb < 4; ++kb)
; #pragma unroll
;         for (int j = 0; j < 4; ++j) s[0][kb][j] = fast_exp2(s[0][kb][j]);
;     { f32x4 t = (s[0][0] + s[0][1]) + (s[0][2] + s[0][3]); ol[0][0] += (t[0] + t[1]) + (t[2] + t[3]); }
;     bf16x8 pf0[2], pf1[2];
; #pragma unroll
;     for (int kk = 0; kk < 2; ++kk) { const u32x4 pw = pack8(s[0][2 * kk], s[0][2 * kk + 1]); pf0[kk] = __builtin_bit_cast(bf16x8, pw); }
;     __builtin_amdgcn_sched_barrier(0);
; #pragma unroll
;     for (int i = 0; i < 16; ++i) {
;         const int db = i >> 1, kk = i & 1;
;         o[0][db] = __builtin_amdgcn_mfma_f32_16x16x32_bf16(vf[db * 2 + kk], pf0[kk], o[0][db], 0, 0, 0);
;         s[1][i >> 2][i & 3] = fast_exp2(s[1][i >> 2][i & 3]);
;         __builtin_amdgcn_sched_barrier(0);
;     }
.LBB0_1342:
	v_max3_f32 v30, v2, v3, v4
	ds_read_b128 v[96:99], v109 offset:57344
	ds_read_b128 v[92:95], v88 offset:57344
	ds_read_b128 v[110:113], v109 offset:59392
	ds_read_b128 v[100:103], v88 offset:59392
	ds_read_b128 v[114:117], v109 offset:61440
	ds_read_b128 v[104:107], v88 offset:61440
	ds_read_b128 v[118:121], v109 offset:63488
	ds_read_b128 v[122:125], v88 offset:63488
	v_max3_f32 v30, v30, v5, v6
	v_max3_f32 v30, v30, v7, v8
	v_max3_f32 v30, v30, v9, v10
	v_max3_f32 v30, v30, v11, v12
	v_max3_f32 v30, v30, v13, v14
	v_max3_f32 v30, v30, v15, v16
	v_max_f32_e32 v30, v30, v17
	v_mov_b32_e32 v31, v30
	s_nop 1
	v_permlane32_swap_b32_e32 v30, v31
	v_max_f32_e32 v30, v30, v31
	v_mov_b32_e32 v31, v30
	s_nop 1
	v_permlane16_swap_b32_e32 v30, v31
	v_max_f32_e32 v213, v30, v31
	v_max3_f32 v30, v18, v19, v20
	v_max3_f32 v30, v30, v21, v22
	v_max3_f32 v30, v30, v23, v24
	v_max3_f32 v30, v30, v25, v26
	v_max3_f32 v30, v30, v27, v28
	v_max3_f32 v30, v30, v29, v76
	v_max3_f32 v30, v30, v77, v78
	v_max_f32_e32 v30, v30, v79
	v_mov_b32_e32 v31, v30
	s_nop 1
	v_permlane32_swap_b32_e32 v30, v31
	v_max_f32_e32 v30, v30, v31
	v_mov_b32_e32 v31, v30
	s_nop 1
	v_permlane16_swap_b32_e32 v30, v31
	v_max_f32_e32 v212, v30, v31
	v_sub_f32_e32 v17, v17, v213
	v_sub_f32_e32 v16, v16, v213
	v_sub_f32_e32 v15, v15, v213
	v_sub_f32_e32 v14, v14, v213
	v_sub_f32_e32 v13, v13, v213
	v_sub_f32_e32 v12, v12, v213
	v_sub_f32_e32 v11, v11, v213
	v_sub_f32_e32 v10, v10, v213
	v_sub_f32_e32 v9, v9, v213
	v_sub_f32_e32 v8, v8, v213
	v_sub_f32_e32 v7, v7, v213
	v_sub_f32_e32 v6, v6, v213
	v_sub_f32_e32 v5, v5, v213
	v_sub_f32_e32 v4, v4, v213
	v_sub_f32_e32 v3, v3, v213
	v_sub_f32_e32 v2, v2, v213
	v_exp_f32_e32 v2, v2
	v_exp_f32_e32 v3, v3
	v_exp_f32_e32 v4, v4
	v_exp_f32_e32 v5, v5
	v_exp_f32_e32 v6, v6
	v_exp_f32_e32 v7, v7
	v_exp_f32_e32 v8, v8
	v_exp_f32_e32 v9, v9
	v_exp_f32_e32 v10, v10
	v_exp_f32_e32 v11, v11
	v_exp_f32_e32 v12, v12
	v_exp_f32_e32 v13, v13
	v_exp_f32_e32 v14, v14
	v_exp_f32_e32 v15, v15
	v_exp_f32_e32 v16, v16
	v_exp_f32_e32 v17, v17
	v_sub_f32_e32 v137, v29, v212
	v_sub_f32_e32 v136, v28, v212
	v_sub_f32_e32 v135, v27, v212
	v_sub_f32_e32 v134, v26, v212
	v_sub_f32_e32 v133, v25, v212
	v_sub_f32_e32 v132, v24, v212
	v_sub_f32_e32 v26, v23, v212
	v_sub_f32_e32 v27, v22, v212
	v_sub_f32_e32 v28, v21, v212
	v_sub_f32_e32 v29, v20, v212
	v_sub_f32_e32 v30, v19, v212
	v_sub_f32_e32 v31, v18, v212
	v_pk_add_f32 v[18:19], v[2:3], v[6:7]
	v_pk_add_f32 v[20:21], v[4:5], v[8:9]
	v_pk_add_f32 v[22:23], v[10:11], v[14:15]
	v_pk_add_f32 v[24:25], v[12:13], v[16:17]
	v_pk_add_f32 v[18:19], v[18:19], v[22:23]
	v_pk_add_f32 v[20:21], v[20:21], v[24:25]
	v_mov_b32_e32 v85, v1
	v_pk_mov_b32 v[22:23], v[18:19], v[20:21] op_sel:[1,0]
	v_mov_b32_e32 v19, v21
	v_pk_add_f32 v[18:19], v[22:23], v[18:19]
	v_mov_b32_e32 v86, v1
	v_add_f32_e32 v18, v18, v19
	v_add_f32_e32 v84, 0, v18
	v_mov_b32_e32 v87, v1
	v_cvt_pk_bf16_f32 v2, v2, v3
	v_cvt_pk_bf16_f32 v3, v4, v5
	v_cvt_pk_bf16_f32 v4, v6, v7
	v_cvt_pk_bf16_f32 v5, v8, v9
	v_cvt_pk_bf16_f32 v88, v10, v11
	v_cvt_pk_bf16_f32 v89, v12, v13
	v_cvt_pk_bf16_f32 v90, v14, v15
	v_cvt_pk_bf16_f32 v91, v16, v17
	v_sub_f32_e32 v109, v79, v212
	v_sub_f32_e32 v140, v78, v212
	v_sub_f32_e32 v139, v77, v212
	v_sub_f32_e32 v138, v76, v212
	v_mfma_f32_16x16x32_bf16 v[6:9], v[48:51], v[2:5], 0
	v_exp_f32_e32 v126, v31
	v_mfma_f32_16x16x32_bf16 v[76:79], v[32:35], v[88:91], v[6:9]
	v_exp_f32_e32 v127, v30
	v_mfma_f32_16x16x32_bf16 v[6:9], v[68:71], v[2:5], 0
	v_exp_f32_e32 v128, v29
	v_exp_f32_e32 v129, v28
	v_mfma_f32_16x16x32_bf16 v[28:31], v[36:39], v[88:91], v[6:9]
	v_mfma_f32_16x16x32_bf16 v[6:9], v[72:75], v[2:5], 0
	v_exp_f32_e32 v130, v27
	v_exp_f32_e32 v131, v26
	v_mfma_f32_16x16x32_bf16 v[24:27], v[40:43], v[88:91], v[6:9]
	v_mfma_f32_16x16x32_bf16 v[6:9], v[80:83], v[2:5], 0
	v_exp_f32_e32 v132, v132
	v_mfma_f32_16x16x32_bf16 v[20:23], v[44:47], v[88:91], v[6:9]
	v_exp_f32_e32 v133, v133
	s_waitcnt lgkmcnt(0)
	v_mfma_f32_16x16x32_bf16 v[6:9], v[96:99], v[2:5], 0
	v_exp_f32_e32 v134, v134
	v_mfma_f32_16x16x32_bf16 v[16:19], v[92:95], v[88:91], v[6:9]
	v_exp_f32_e32 v135, v135
	v_mfma_f32_16x16x32_bf16 v[6:9], v[110:113], v[2:5], 0
	v_exp_f32_e32 v136, v136
	v_mfma_f32_16x16x32_bf16 v[12:15], v[100:103], v[88:91], v[6:9]
	v_exp_f32_e32 v137, v137
	v_mfma_f32_16x16x32_bf16 v[6:9], v[114:117], v[2:5], 0
	v_exp_f32_e32 v138, v138
	v_mfma_f32_16x16x32_bf16 v[8:11], v[104:107], v[88:91], v[6:9]
	v_exp_f32_e32 v139, v139
	v_mfma_f32_16x16x32_bf16 v[2:5], v[118:121], v[2:5], 0
	v_exp_f32_e32 v140, v140
	v_mfma_f32_16x16x32_bf16 v[4:7], v[122:125], v[88:91], v[2:5]
	v_exp_f32_e32 v141, v109
	s_nop 4
	v_pk_add_f32 v[2:3], v[126:127], v[130:131]
	v_pk_add_f32 v[88:89], v[128:129], v[132:133]
	v_pk_add_f32 v[90:91], v[134:135], v[138:139]
	v_pk_add_f32 v[142:143], v[136:137], v[140:141]
	v_pk_add_f32 v[2:3], v[2:3], v[90:91]
	v_pk_add_f32 v[88:89], v[88:89], v[142:143]
	v_cvt_pk_bf16_f32 v126, v126, v127
	v_pk_mov_b32 v[90:91], v[2:3], v[88:89] op_sel:[1,0]
	v_mov_b32_e32 v3, v89
	v_pk_add_f32 v[2:3], v[90:91], v[2:3]
	v_mov_b32_e32 v89, v1
	v_add_f32_e32 v2, v2, v3
	v_add_f32_e32 v88, 0, v2
	v_mov_b32_e32 v90, v1
	v_mov_b32_e32 v91, v1
	v_cvt_pk_bf16_f32 v127, v128, v129
	v_cvt_pk_bf16_f32 v128, v130, v131
	v_cvt_pk_bf16_f32 v129, v132, v133
	v_cvt_pk_bf16_f32 v130, v134, v135
	v_cvt_pk_bf16_f32 v131, v136, v137
	v_cvt_pk_bf16_f32 v132, v138, v139
	v_cvt_pk_bf16_f32 v133, v140, v141
	v_mfma_f32_16x16x32_bf16 v[48:51], v[48:51], v[126:129], 0
	v_mfma_f32_16x16x32_bf16 v[68:71], v[68:71], v[126:129], 0
	v_mfma_f32_16x16x32_bf16 v[134:137], v[72:75], v[126:129], 0
	v_mfma_f32_16x16x32_bf16 v[138:141], v[80:83], v[126:129], 0
	v_mfma_f32_16x16x32_bf16 v[96:99], v[96:99], v[126:129], 0
	v_mfma_f32_16x16x32_bf16 v[110:113], v[110:113], v[126:129], 0
	v_mfma_f32_16x16x32_bf16 v[114:117], v[114:117], v[126:129], 0
	v_mfma_f32_16x16x32_bf16 v[118:121], v[118:121], v[126:129], 0
	v_mfma_f32_16x16x32_bf16 v[80:83], v[32:35], v[130:133], v[48:51]
	v_mfma_f32_16x16x32_bf16 v[72:75], v[36:39], v[130:133], v[68:71]
	v_mfma_f32_16x16x32_bf16 v[68:71], v[40:43], v[130:133], v[134:137]
	v_mfma_f32_16x16x32_bf16 v[48:51], v[44:47], v[130:133], v[138:141]
	v_mfma_f32_16x16x32_bf16 v[44:47], v[92:95], v[130:133], v[96:99]
	v_mfma_f32_16x16x32_bf16 v[40:43], v[100:103], v[130:133], v[110:113]
	v_mfma_f32_16x16x32_bf16 v[36:39], v[104:107], v[130:133], v[114:117]
	v_mfma_f32_16x16x32_bf16 v[32:35], v[122:125], v[130:133], v[118:121]
	s_mov_b64 s[8:9], 0

; __device__ __forceinline__ void attn_qblock(int b, int h, int q0, float lam, LAS unsigned char* lds, const bf16_t* qbuf, const bf16_t* kbuf, const bf16_t* vT, bf16_t* mix, const float* bias_g, const float* ssm_sq, bool var) {
;     ...
;     AT_STAGE(0, 0);
;     asm volatile("s_waitcnt vmcnt(0)" ::: "memory");
;     __syncthreads();
;     const float cfar = biasl[128];
;     int cur = 0;
;     for (int kt = 0; kt < ntiles; ++kt) {
;         const int k0 = kt * 64, nxt = (cur == AT_NBUF - 1) ? 0 : cur + 1;
;         if (kt + 1 < ntiles) AT_STAGE(nxt, k0 + 64);
;         if (k0 <= qw0 + 15) at_tile(lds + AT_K0 + cur * AT_KBUF, lds + AT_V0 + cur * AT_VBUF, biasl, r, g, k0, qw0, qrow, cfar, qf, mrow, ol, o, kt == 0);
;         asm volatile("s_waitcnt vmcnt(0)" ::: "memory");
;         __syncthreads();
;         cur = nxt;
.LBB0_1346:
	s_add_i32 s9, s8, 1
	s_cmp_lg_u32 s8, 2
	s_cselect_b32 s39, s9, 0
	s_add_i32 s33, s33, 1
	s_cmp_ge_i32 s33, s24
	s_cbranch_scc1 .LBB0_1348
	s_lshl_b64 s[44:45], s[18:19], 10
	s_add_u32 s44, s48, s44
	s_addc_u32 s45, s49, s45
	s_lshl_b32 s9, s39, 14
	s_lshl_b64 s[46:47], s[18:19], 1
	s_add_u32 s46, s52, s46
	s_addc_u32 s47, s53, s47
	s_add_i32 s9, s22, s9
	s_mov_b32 m0, s9
	s_nop 0
	global_load_lds_dwordx4 v0, s[44:45]
	s_add_i32 m0, s9, 0xc000
	s_nop 0
	global_load_lds_dwordx4 v206, s[46:47]
	s_add_i32 m0, s9, 0x2000
	s_nop 0
	global_load_lds_dwordx4 v208, s[44:45]
	s_add_i32 m0, s9, 0xe000
	s_nop 0
	global_load_lds_dwordx4 v210, s[46:47]

; #define LAS __attribute__((address_space(3)))
; __device__ __forceinline__ float max3f(float a, float b, float c) { float r; asm("v_max3_f32 %0, %1, %2, %3" : "=v"(r) : "v"(a), "v"(b), "v"(c)); return r; }
; __device__ __forceinline__ float max2f(float a, float b) { float r; asm("v_max_f32_e32 %0, %1, %2" : "=v"(r) : "v"(a), "v"(b)); return r; }
; __device__ __forceinline__ float fast_exp2(float x) { return __builtin_amdgcn_exp2f(x); }
; __device__ __forceinline__ void at_tile(LAS unsigned char* Kb, LAS unsigned char* Vb, const LAS float* biasl, int r, int g, int k0, int qw0, int qrow, float cfar,
;                                         const bf16x8 (&qf)[2][2], float (&mrow)[2], f32x4 (&ol)[2], f32x4 (&o)[2][8], bool first) {
;     ...
;     float mx[2];
; #pragma unroll
;     for (int m = 0; m < 2; ++m) {
;         float v = max3f(s[m][0][0], s[m][0][1], s[m][0][2]);
;         v = max3f(v, s[m][0][3], s[m][1][0]); v = max3f(v, s[m][1][1], s[m][1][2]); v = max3f(v, s[m][1][3], s[m][2][0]);
;         v = max3f(v, s[m][2][1], s[m][2][2]); v = max3f(v, s[m][2][3], s[m][3][0]); v = max3f(v, s[m][3][1], s[m][3][2]); v = max2f(v, s[m][3][3]);
;         mx[m] = xl_max(v);
;     }
; #pragma unroll
;     for (int db = 4; db < 8; ++db)
; #pragma unroll
;         for (int kk = 0; kk < 2; ++kk) vf[db * 2 + kk] = *(const LAS bf16x8*)(Vb + (db * 16 + r) * AT_VROW + (((kk * 4 + g) ^ (r >> 1)) * 16));
;     __builtin_amdgcn_sched_barrier(0);
;     if (first || __any(max2f(mx[0], mx[1]) > 10.0f)) {
; #pragma unroll
;         for (int m = 0; m < 2; ++m) {
;             const float delta = first ? mx[m] : fmaxf(mx[m], 0.f), alpha = first ? 0.f : fast_exp2(-delta);
;             mrow[m] = first ? delta : mrow[m] + delta;
;             ol[m] = ol[m] * alpha;
; #pragma unroll
;             for (int db = 0; db < 8; ++db) o[m][db] = o[m][db] * alpha;
; #pragma unroll
;             for (int kb = 0; kb < 4; ++kb) s[m][kb] = s[m][kb] - delta;
;         }
;     }
.LBB0_1353:
	v_max3_f32 v2, v152, v153, v154
	v_max3_f32 v2, v2, v155, v148
	v_max3_f32 v2, v2, v149, v150
	v_max3_f32 v2, v2, v151, v144
	v_max3_f32 v2, v2, v145, v146
	v_max3_f32 v2, v2, v147, v140
	v_max3_f32 v2, v2, v141, v142
	v_max_f32_e32 v2, v2, v143
	v_mov_b32_e32 v156, v2
	s_nop 1
	v_permlane32_swap_b32_e32 v2, v156
	v_max_f32_e32 v2, v2, v156
	v_mov_b32_e32 v156, v2
	s_nop 1
	v_permlane16_swap_b32_e32 v2, v156
	v_max_f32_e32 v247, v2, v156
	v_max3_f32 v2, v136, v137, v138
	v_max3_f32 v2, v2, v139, v132
	v_max3_f32 v2, v2, v133, v134
	v_max3_f32 v2, v2, v135, v128
	v_max3_f32 v2, v2, v129, v130
	v_max3_f32 v2, v2, v131, v124
	v_max3_f32 v2, v2, v125, v126
	v_max_f32_e32 v2, v2, v127
	v_mov_b32_e32 v156, v2
	s_nop 1
	v_permlane32_swap_b32_e32 v2, v156
	v_max_f32_e32 v2, v2, v156
	v_mov_b32_e32 v156, v2
	s_nop 1
	v_permlane16_swap_b32_e32 v2, v156
	v_max_f32_e32 v2, v2, v156
	ds_read_b128 v[160:163], v181 offset:57344
	ds_read_b128 v[156:159], v180 offset:57344
	ds_read_b128 v[172:175], v181 offset:59392
	ds_read_b128 v[164:167], v180 offset:59392
	ds_read_b128 v[176:179], v181 offset:61440
	ds_read_b128 v[168:171], v180 offset:61440
	ds_read_b128 v[184:187], v181 offset:63488
	ds_read_b128 v[180:183], v180 offset:63488
	v_max_f32_e32 v188, v247, v2
	v_cmp_lt_f32_e32 vcc, s84, v188
	s_cbranch_vccz .LBB0_1355
	v_max_f32_e32 v188, v247, v247
	v_max_f32_e32 v189, 0, v188
	v_exp_f32_e64 v188, -v189
	v_max_f32_e32 v2, v2, v2
	v_sub_f32_e32 v152, v152, v189
	v_sub_f32_e32 v153, v153, v189
	v_pk_mul_f32 v[86:87], v[86:87], v[188:189] op_sel_hi:[1,0]
	v_pk_mul_f32 v[84:85], v[84:85], v[188:189] op_sel_hi:[1,0]
	v_pk_mul_f32 v[78:79], v[78:79], v[188:189] op_sel_hi:[1,0]
	v_pk_mul_f32 v[76:77], v[76:77], v[188:189] op_sel_hi:[1,0]
	v_pk_mul_f32 v[30:31], v[30:31], v[188:189] op_sel_hi:[1,0]
	v_pk_mul_f32 v[28:29], v[28:29], v[188:189] op_sel_hi:[1,0]
	v_pk_mul_f32 v[26:27], v[26:27], v[188:189] op_sel_hi:[1,0]
	v_pk_mul_f32 v[24:25], v[24:25], v[188:189] op_sel_hi:[1,0]
	v_pk_mul_f32 v[22:23], v[22:23], v[188:189] op_sel_hi:[1,0]
	v_pk_mul_f32 v[20:21], v[20:21], v[188:189] op_sel_hi:[1,0]
	v_pk_mul_f32 v[18:19], v[18:19], v[188:189] op_sel_hi:[1,0]
	v_pk_mul_f32 v[16:17], v[16:17], v[188:189] op_sel_hi:[1,0]
	v_pk_mul_f32 v[14:15], v[14:15], v[188:189] op_sel_hi:[1,0]
	v_pk_mul_f32 v[12:13], v[12:13], v[188:189] op_sel_hi:[1,0]
	v_pk_mul_f32 v[10:11], v[10:11], v[188:189] op_sel_hi:[1,0]
	v_pk_mul_f32 v[8:9], v[8:9], v[188:189] op_sel_hi:[1,0]
	v_pk_mul_f32 v[6:7], v[6:7], v[188:189] op_sel_hi:[1,0]
	v_pk_mul_f32 v[4:5], v[4:5], v[188:189] op_sel_hi:[1,0]
	v_max_f32_e32 v188, 0, v2
	v_exp_f32_e64 v2, -v188
	v_sub_f32_e32 v154, v154, v189
	v_sub_f32_e32 v155, v155, v189
	v_sub_f32_e32 v148, v148, v189
	v_sub_f32_e32 v149, v149, v189
	v_sub_f32_e32 v150, v150, v189
	v_sub_f32_e32 v151, v151, v189
	v_sub_f32_e32 v144, v144, v189
	v_sub_f32_e32 v145, v145, v189
	v_sub_f32_e32 v146, v146, v189
	v_sub_f32_e32 v147, v147, v189
	v_sub_f32_e32 v140, v140, v189
	v_sub_f32_e32 v141, v141, v189
	v_sub_f32_e32 v142, v142, v189
	v_sub_f32_e32 v143, v143, v189
	v_pk_add_f32 v[212:213], v[212:213], v[188:189]
	v_pk_mul_f32 v[90:91], v[90:91], v[2:3] op_sel_hi:[1,0]
	v_pk_mul_f32 v[88:89], v[88:89], v[2:3] op_sel_hi:[1,0]
	v_pk_mul_f32 v[82:83], v[82:83], v[2:3] op_sel_hi:[1,0]
	v_pk_mul_f32 v[80:81], v[80:81], v[2:3] op_sel_hi:[1,0]
	v_pk_mul_f32 v[74:75], v[74:75], v[2:3] op_sel_hi:[1,0]
	v_pk_mul_f32 v[72:73], v[72:73], v[2:3] op_sel_hi:[1,0]
	v_pk_mul_f32 v[70:71], v[70:71], v[2:3] op_sel_hi:[1,0]
	v_pk_mul_f32 v[68:69], v[68:69], v[2:3] op_sel_hi:[1,0]
	v_pk_mul_f32 v[50:51], v[50:51], v[2:3] op_sel_hi:[1,0]
	v_pk_mul_f32 v[48:49], v[48:49], v[2:3] op_sel_hi:[1,0]
	v_pk_mul_f32 v[46:47], v[46:47], v[2:3] op_sel_hi:[1,0]
	v_pk_mul_f32 v[44:45], v[44:45], v[2:3] op_sel_hi:[1,0]
	v_pk_mul_f32 v[42:43], v[42:43], v[2:3] op_sel_hi:[1,0]
	v_pk_mul_f32 v[40:41], v[40:41], v[2:3] op_sel_hi:[1,0]
	v_pk_mul_f32 v[38:39], v[38:39], v[2:3] op_sel_hi:[1,0]
	v_pk_mul_f32 v[36:37], v[36:37], v[2:3] op_sel_hi:[1,0]
	v_pk_mul_f32 v[34:35], v[34:35], v[2:3] op_sel_hi:[1,0]
	v_pk_mul_f32 v[32:33], v[32:33], v[2:3] op_sel_hi:[1,0]
	v_sub_f32_e32 v136, v136, v188
	v_sub_f32_e32 v137, v137, v188
	v_sub_f32_e32 v138, v138, v188
	v_sub_f32_e32 v139, v139, v188
	v_sub_f32_e32 v132, v132, v188
	v_sub_f32_e32 v133, v133, v188
	v_sub_f32_e32 v134, v134, v188
	v_sub_f32_e32 v135, v135, v188
	v_sub_f32_e32 v128, v128, v188
	v_sub_f32_e32 v129, v129, v188
	v_sub_f32_e32 v130, v130, v188
	v_sub_f32_e32 v131, v131, v188
	v_sub_f32_e32 v124, v124, v188
	v_sub_f32_e32 v125, v125, v188
	v_sub_f32_e32 v126, v126, v188
	v_sub_f32_e32 v127, v127, v188

; #define LAS __attribute__((address_space(3)))
; __device__ __forceinline__ void at_tile(LAS unsigned char* Kb, LAS unsigned char* Vb, const LAS float* biasl, int r, int g, int k0, int qw0, int qrow, float cfar,
;                                         const bf16x8 (&qf)[2][2], float (&mrow)[2], f32x4 (&ol)[2], f32x4 (&o)[2][8], bool first) {
;     ...
;     float mx[2];
; #pragma unroll
;     for (int m = 0; m < 2; ++m) {
;         float v = max3f(s[m][0][0], s[m][0][1], s[m][0][2]);
;         v = max3f(v, s[m][0][3], s[m][1][0]); v = max3f(v, s[m][1][1], s[m][1][2]); v = max3f(v, s[m][1][3], s[m][2][0]);
;         v = max3f(v, s[m][2][1], s[m][2][2]); v = max3f(v, s[m][2][3], s[m][3][0]); v = max3f(v, s[m][3][1], s[m][3][2]); v = max2f(v, s[m][3][3]);
;         mx[m] = xl_max(v);
;     }
; #pragma unroll
;     for (int db = 4; db < 8; ++db)
; #pragma unroll
;         for (int kk = 0; kk < 2; ++kk) vf[db * 2 + kk] = *(const LAS bf16x8*)(Vb + (db * 16 + r) * AT_VROW + (((kk * 4 + g) ^ (r >> 1)) * 16));
;     __builtin_amdgcn_sched_barrier(0);
;     if (first || __any(max2f(mx[0], mx[1]) > 10.0f)) {
; #pragma unroll
;         for (int m = 0; m < 2; ++m) {
;             const float delta = first ? mx[m] : fmaxf(mx[m], 0.f), alpha = first ? 0.f : fast_exp2(-delta);
;             mrow[m] = first ? delta : mrow[m] + delta;
;             ol[m] = ol[m] * alpha;
; #pragma unroll
;             for (int db = 0; db < 8; ++db) o[m][db] = o[m][db] * alpha;
; #pragma unroll
;             for (int kb = 0; kb < 4; ++kb) s[m][kb] = s[m][kb] - delta;
;         }
;     }
; #pragma unroll
;     for (int kb = 0; kb < 4; ++kb)
; #pragma unroll
;         for (int j = 0; j < 4; ++j) s[0][kb][j] = fast_exp2(s[0][kb][j]);
;     { f32x4 t = (s[0][0] + s[0][1]) + (s[0][2] + s[0][3]); ol[0][0] += (t[0] + t[1]) + (t[2] + t[3]); }
;     bf16x8 pf0[2], pf1[2];
; #pragma unroll
;     for (int kk = 0; kk < 2; ++kk) { const u32x4 pw = pack8(s[0][2 * kk], s[0][2 * kk + 1]); pf0[kk] = __builtin_bit_cast(bf16x8, pw); }
;     __builtin_amdgcn_sched_barrier(0);
; #pragma unroll
;     for (int i = 0; i < 16; ++i) {
;         const int db = i >> 1, kk = i & 1;
;         o[0][db] = __builtin_amdgcn_mfma_f32_16x16x32_bf16(vf[db * 2 + kk], pf0[kk], o[0][db], 0, 0, 0);
;         s[1][i >> 2][i & 3] = fast_exp2(s[1][i >> 2][i & 3]);
;         __builtin_amdgcn_sched_barrier(0);
;     }
.LBB0_1367:
	v_max3_f32 v30, v2, v3, v4
	ds_read_b128 v[96:99], v109 offset:57344
	ds_read_b128 v[92:95], v88 offset:57344
	ds_read_b128 v[110:113], v109 offset:59392
	ds_read_b128 v[100:103], v88 offset:59392
	ds_read_b128 v[114:117], v109 offset:61440
	ds_read_b128 v[104:107], v88 offset:61440
	ds_read_b128 v[118:121], v109 offset:63488
	ds_read_b128 v[122:125], v88 offset:63488
	v_max3_f32 v30, v30, v5, v6
	v_max3_f32 v30, v30, v7, v8
	v_max3_f32 v30, v30, v9, v10
	v_max3_f32 v30, v30, v11, v12
	v_max3_f32 v30, v30, v13, v14
	v_max3_f32 v30, v30, v15, v16
	v_max_f32_e32 v30, v30, v17
	v_mov_b32_e32 v31, v30
	s_nop 1
	v_permlane32_swap_b32_e32 v30, v31
	v_max_f32_e32 v30, v30, v31
	v_mov_b32_e32 v31, v30
	s_nop 1
	v_permlane16_swap_b32_e32 v30, v31
	v_max_f32_e32 v213, v30, v31
	v_max3_f32 v30, v18, v19, v20
	v_max3_f32 v30, v30, v21, v22
	v_max3_f32 v30, v30, v23, v24
	v_max3_f32 v30, v30, v25, v26
	v_max3_f32 v30, v30, v27, v28
	v_max3_f32 v30, v30, v29, v76
	v_max3_f32 v30, v30, v77, v78
	v_max_f32_e32 v30, v30, v79
	v_mov_b32_e32 v31, v30
	s_nop 1
	v_permlane32_swap_b32_e32 v30, v31
	v_max_f32_e32 v30, v30, v31
	v_mov_b32_e32 v31, v30
	s_nop 1
	v_permlane16_swap_b32_e32 v30, v31
	v_max_f32_e32 v212, v30, v31
	v_sub_f32_e32 v17, v17, v213
	v_sub_f32_e32 v16, v16, v213
	v_sub_f32_e32 v15, v15, v213
	v_sub_f32_e32 v14, v14, v213
	v_sub_f32_e32 v13, v13, v213
	v_sub_f32_e32 v12, v12, v213
	v_sub_f32_e32 v11, v11, v213
	v_sub_f32_e32 v10, v10, v213
	v_sub_f32_e32 v9, v9, v213
	v_sub_f32_e32 v8, v8, v213
	v_sub_f32_e32 v7, v7, v213
	v_sub_f32_e32 v6, v6, v213
	v_sub_f32_e32 v5, v5, v213
	v_sub_f32_e32 v4, v4, v213
	v_sub_f32_e32 v3, v3, v213
	v_sub_f32_e32 v2, v2, v213
	v_exp_f32_e32 v2, v2
	v_exp_f32_e32 v3, v3
	v_exp_f32_e32 v4, v4
	v_exp_f32_e32 v5, v5
	v_exp_f32_e32 v6, v6
	v_exp_f32_e32 v7, v7
	v_exp_f32_e32 v8, v8
	v_exp_f32_e32 v9, v9
	v_exp_f32_e32 v10, v10
	v_exp_f32_e32 v11, v11
	v_exp_f32_e32 v12, v12
	v_exp_f32_e32 v13, v13
	v_exp_f32_e32 v14, v14
	v_exp_f32_e32 v15, v15
	v_exp_f32_e32 v16, v16
	v_exp_f32_e32 v17, v17
	v_sub_f32_e32 v137, v29, v212
	v_sub_f32_e32 v136, v28, v212
	v_sub_f32_e32 v135, v27, v212
	v_sub_f32_e32 v134, v26, v212
	v_sub_f32_e32 v133, v25, v212
	v_sub_f32_e32 v132, v24, v212
	v_sub_f32_e32 v26, v23, v212
	v_sub_f32_e32 v27, v22, v212
	v_sub_f32_e32 v28, v21, v212
	v_sub_f32_e32 v29, v20, v212
	v_sub_f32_e32 v30, v19, v212
	v_sub_f32_e32 v31, v18, v212
	v_pk_add_f32 v[18:19], v[2:3], v[6:7]
	v_pk_add_f32 v[20:21], v[4:5], v[8:9]
	v_pk_add_f32 v[22:23], v[10:11], v[14:15]
	v_pk_add_f32 v[24:25], v[12:13], v[16:17]
	v_pk_add_f32 v[18:19], v[18:19], v[22:23]
	v_pk_add_f32 v[20:21], v[20:21], v[24:25]
	v_mov_b32_e32 v85, v1
	v_pk_mov_b32 v[22:23], v[18:19], v[20:21] op_sel:[1,0]
	v_mov_b32_e32 v19, v21
	v_pk_add_f32 v[18:19], v[22:23], v[18:19]
	v_mov_b32_e32 v86, v1
	v_add_f32_e32 v18, v18, v19
	v_add_f32_e32 v84, 0, v18
	v_mov_b32_e32 v87, v1
	v_cvt_pk_bf16_f32 v2, v2, v3
	v_cvt_pk_bf16_f32 v3, v4, v5
	v_cvt_pk_bf16_f32 v4, v6, v7
	v_cvt_pk_bf16_f32 v5, v8, v9
	v_cvt_pk_bf16_f32 v88, v10, v11
	v_cvt_pk_bf16_f32 v89, v12, v13
	v_cvt_pk_bf16_f32 v90, v14, v15
	v_cvt_pk_bf16_f32 v91, v16, v17
	v_sub_f32_e32 v109, v79, v212
	v_sub_f32_e32 v140, v78, v212
	v_sub_f32_e32 v139, v77, v212
	v_sub_f32_e32 v138, v76, v212
	v_mfma_f32_16x16x32_bf16 v[6:9], v[48:51], v[2:5], 0
	v_exp_f32_e32 v126, v31
	v_mfma_f32_16x16x32_bf16 v[76:79], v[32:35], v[88:91], v[6:9]
	v_exp_f32_e32 v127, v30
	v_mfma_f32_16x16x32_bf16 v[6:9], v[52:55], v[2:5], 0
	v_exp_f32_e32 v128, v29
	v_exp_f32_e32 v129, v28
	v_mfma_f32_16x16x32_bf16 v[28:31], v[36:39], v[88:91], v[6:9]
	v_mfma_f32_16x16x32_bf16 v[6:9], v[72:75], v[2:5], 0
	v_exp_f32_e32 v130, v27
	v_exp_f32_e32 v131, v26
	v_mfma_f32_16x16x32_bf16 v[24:27], v[40:43], v[88:91], v[6:9]
	v_mfma_f32_16x16x32_bf16 v[6:9], v[80:83], v[2:5], 0
	v_exp_f32_e32 v132, v132
	v_mfma_f32_16x16x32_bf16 v[20:23], v[44:47], v[88:91], v[6:9]
	v_exp_f32_e32 v133, v133
	s_waitcnt lgkmcnt(0)
	v_mfma_f32_16x16x32_bf16 v[6:9], v[96:99], v[2:5], 0
	v_exp_f32_e32 v134, v134
	v_mfma_f32_16x16x32_bf16 v[16:19], v[92:95], v[88:91], v[6:9]
	v_exp_f32_e32 v135, v135
	v_mfma_f32_16x16x32_bf16 v[6:9], v[110:113], v[2:5], 0
	v_exp_f32_e32 v136, v136
	v_mfma_f32_16x16x32_bf16 v[12:15], v[100:103], v[88:91], v[6:9]
	v_exp_f32_e32 v137, v137
	v_mfma_f32_16x16x32_bf16 v[6:9], v[114:117], v[2:5], 0
	v_exp_f32_e32 v138, v138
	v_mfma_f32_16x16x32_bf16 v[8:11], v[104:107], v[88:91], v[6:9]
	v_exp_f32_e32 v139, v139
	v_mfma_f32_16x16x32_bf16 v[2:5], v[118:121], v[2:5], 0
	v_exp_f32_e32 v140, v140
	v_mfma_f32_16x16x32_bf16 v[4:7], v[122:125], v[88:91], v[2:5]
	v_exp_f32_e32 v141, v109
	s_nop 4
	v_pk_add_f32 v[2:3], v[126:127], v[130:131]
	v_pk_add_f32 v[88:89], v[128:129], v[132:133]
	v_pk_add_f32 v[90:91], v[134:135], v[138:139]
	v_pk_add_f32 v[142:143], v[136:137], v[140:141]
	v_pk_add_f32 v[2:3], v[2:3], v[90:91]
	v_pk_add_f32 v[88:89], v[88:89], v[142:143]
	v_cvt_pk_bf16_f32 v126, v126, v127
	v_pk_mov_b32 v[90:91], v[2:3], v[88:89] op_sel:[1,0]
	v_mov_b32_e32 v3, v89
	v_pk_add_f32 v[2:3], v[90:91], v[2:3]
	v_mov_b32_e32 v89, v1
	v_add_f32_e32 v2, v2, v3
	v_add_f32_e32 v88, 0, v2
	v_mov_b32_e32 v90, v1
	v_mov_b32_e32 v91, v1
	v_cvt_pk_bf16_f32 v127, v128, v129
	v_cvt_pk_bf16_f32 v128, v130, v131
	v_cvt_pk_bf16_f32 v129, v132, v133
	v_cvt_pk_bf16_f32 v130, v134, v135
	v_cvt_pk_bf16_f32 v131, v136, v137
	v_cvt_pk_bf16_f32 v132, v138, v139
	v_cvt_pk_bf16_f32 v133, v140, v141
	v_mfma_f32_16x16x32_bf16 v[48:51], v[48:51], v[126:129], 0
	v_mfma_f32_16x16x32_bf16 v[52:55], v[52:55], v[126:129], 0
	v_mfma_f32_16x16x32_bf16 v[134:137], v[72:75], v[126:129], 0
	v_mfma_f32_16x16x32_bf16 v[138:141], v[80:83], v[126:129], 0
	v_mfma_f32_16x16x32_bf16 v[96:99], v[96:99], v[126:129], 0
	v_mfma_f32_16x16x32_bf16 v[110:113], v[110:113], v[126:129], 0
	v_mfma_f32_16x16x32_bf16 v[114:117], v[114:117], v[126:129], 0
	v_mfma_f32_16x16x32_bf16 v[118:121], v[118:121], v[126:129], 0
	v_mfma_f32_16x16x32_bf16 v[80:83], v[32:35], v[130:133], v[48:51]
	v_mfma_f32_16x16x32_bf16 v[72:75], v[36:39], v[130:133], v[52:55]
	v_mfma_f32_16x16x32_bf16 v[52:55], v[40:43], v[130:133], v[134:137]
	v_mfma_f32_16x16x32_bf16 v[48:51], v[44:47], v[130:133], v[138:141]
	v_mfma_f32_16x16x32_bf16 v[44:47], v[92:95], v[130:133], v[96:99]
	v_mfma_f32_16x16x32_bf16 v[40:43], v[100:103], v[130:133], v[110:113]
	v_mfma_f32_16x16x32_bf16 v[36:39], v[104:107], v[130:133], v[114:117]
	v_mfma_f32_16x16x32_bf16 v[32:35], v[122:125], v[130:133], v[118:121]
	s_mov_b64 s[8:9], 0

; __device__ __forceinline__ void attn_qblock(int b, int h, int q0, float lam, LAS unsigned char* lds, const bf16_t* qbuf, const bf16_t* kbuf, const bf16_t* vT, bf16_t* mix, const float* bias_g, const float* ssm_sq, bool var) {
;     ...
;     AT_STAGE(0, 0);
;     asm volatile("s_waitcnt vmcnt(0)" ::: "memory");
;     __syncthreads();
;     const float cfar = biasl[128];
;     int cur = 0;
;     for (int kt = 0; kt < ntiles; ++kt) {
;         const int k0 = kt * 64, nxt = (cur == AT_NBUF - 1) ? 0 : cur + 1;
;         if (kt + 1 < ntiles) AT_STAGE(nxt, k0 + 64);
;         if (k0 <= qw0 + 15) at_tile(lds + AT_K0 + cur * AT_KBUF, lds + AT_V0 + cur * AT_VBUF, biasl, r, g, k0, qw0, qrow, cfar, qf, mrow, ol, o, kt == 0);
;         asm volatile("s_waitcnt vmcnt(0)" ::: "memory");
;         __syncthreads();
;         cur = nxt;
.LBB0_1371:
	s_add_i32 s9, s8, 1
	s_cmp_lg_u32 s8, 2
	s_cselect_b32 s24, s9, 0
	s_add_i32 s22, s22, 1
	s_cmp_ge_i32 s22, s2
	s_cbranch_scc1 .LBB0_1373
	s_lshl_b64 s[44:45], s[18:19], 10
	s_add_u32 s44, s48, s44
	s_addc_u32 s45, s49, s45
	s_lshl_b32 s9, s24, 14
	s_lshl_b64 s[46:47], s[18:19], 1
	s_add_u32 s46, s52, s46
	s_addc_u32 s47, s53, s47
	s_add_i32 s9, s4, s9
	s_mov_b32 m0, s9
	s_nop 0
	global_load_lds_dwordx4 v0, s[44:45]
	s_add_i32 m0, s9, 0xc000
	s_nop 0
	global_load_lds_dwordx4 v206, s[46:47]
	s_add_i32 m0, s9, 0x2000
	s_nop 0
	global_load_lds_dwordx4 v208, s[44:45]
	s_add_i32 m0, s9, 0xe000
	s_nop 0
	global_load_lds_dwordx4 v210, s[46:47]

; #define LAS __attribute__((address_space(3)))
; __device__ __forceinline__ float max3f(float a, float b, float c) { float r; asm("v_max3_f32 %0, %1, %2, %3" : "=v"(r) : "v"(a), "v"(b), "v"(c)); return r; }
; __device__ __forceinline__ float max2f(float a, float b) { float r; asm("v_max_f32_e32 %0, %1, %2" : "=v"(r) : "v"(a), "v"(b)); return r; }
; __device__ __forceinline__ float fast_exp2(float x) { return __builtin_amdgcn_exp2f(x); }
; __device__ __forceinline__ void at_tile(LAS unsigned char* Kb, LAS unsigned char* Vb, const LAS float* biasl, int r, int g, int k0, int qw0, int qrow, float cfar,
;                                         const bf16x8 (&qf)[2][2], float (&mrow)[2], f32x4 (&ol)[2], f32x4 (&o)[2][8], bool first) {
;     ...
;     float mx[2];
; #pragma unroll
;     for (int m = 0; m < 2; ++m) {
;         float v = max3f(s[m][0][0], s[m][0][1], s[m][0][2]);
;         v = max3f(v, s[m][0][3], s[m][1][0]); v = max3f(v, s[m][1][1], s[m][1][2]); v = max3f(v, s[m][1][3], s[m][2][0]);
;         v = max3f(v, s[m][2][1], s[m][2][2]); v = max3f(v, s[m][2][3], s[m][3][0]); v = max3f(v, s[m][3][1], s[m][3][2]); v = max2f(v, s[m][3][3]);
;         mx[m] = xl_max(v);
;     }
; #pragma unroll
;     for (int db = 4; db < 8; ++db)
; #pragma unroll
;         for (int kk = 0; kk < 2; ++kk) vf[db * 2 + kk] = *(const LAS bf16x8*)(Vb + (db * 16 + r) * AT_VROW + (((kk * 4 + g) ^ (r >> 1)) * 16));
;     __builtin_amdgcn_sched_barrier(0);
;     if (first || __any(max2f(mx[0], mx[1]) > 10.0f)) {
; #pragma unroll
;         for (int m = 0; m < 2; ++m) {
;             const float delta = first ? mx[m] : fmaxf(mx[m], 0.f), alpha = first ? 0.f : fast_exp2(-delta);
;             mrow[m] = first ? delta : mrow[m] + delta;
;             ol[m] = ol[m] * alpha;
; #pragma unroll
;             for (int db = 0; db < 8; ++db) o[m][db] = o[m][db] * alpha;
; #pragma unroll
;             for (int kb = 0; kb < 4; ++kb) s[m][kb] = s[m][kb] - delta;
;         }
;     }
.LBB0_1378:
	v_max3_f32 v2, v152, v153, v154
	v_max3_f32 v2, v2, v155, v148
	v_max3_f32 v2, v2, v149, v150
	v_max3_f32 v2, v2, v151, v144
	v_max3_f32 v2, v2, v145, v146
	v_max3_f32 v2, v2, v147, v140
	v_max3_f32 v2, v2, v141, v142
	v_max_f32_e32 v2, v2, v143
	v_mov_b32_e32 v156, v2
	s_nop 1
	v_permlane32_swap_b32_e32 v2, v156
	v_max_f32_e32 v2, v2, v156
	v_mov_b32_e32 v156, v2
	s_nop 1
	v_permlane16_swap_b32_e32 v2, v156
	v_max_f32_e32 v247, v2, v156
	v_max3_f32 v2, v136, v137, v138
	v_max3_f32 v2, v2, v139, v132
	v_max3_f32 v2, v2, v133, v134
	v_max3_f32 v2, v2, v135, v128
	v_max3_f32 v2, v2, v129, v130
	v_max3_f32 v2, v2, v131, v124
	v_max3_f32 v2, v2, v125, v126
	v_max_f32_e32 v2, v2, v127
	v_mov_b32_e32 v156, v2
	s_nop 1
	v_permlane32_swap_b32_e32 v2, v156
	v_max_f32_e32 v2, v2, v156
	v_mov_b32_e32 v156, v2
	s_nop 1
	v_permlane16_swap_b32_e32 v2, v156
	v_max_f32_e32 v2, v2, v156
	ds_read_b128 v[160:163], v181 offset:57344
	ds_read_b128 v[156:159], v180 offset:57344
	ds_read_b128 v[172:175], v181 offset:59392
	ds_read_b128 v[164:167], v180 offset:59392
	ds_read_b128 v[176:179], v181 offset:61440
	ds_read_b128 v[168:171], v180 offset:61440
	ds_read_b128 v[184:187], v181 offset:63488
	ds_read_b128 v[180:183], v180 offset:63488
	v_max_f32_e32 v188, v247, v2
	v_cmp_lt_f32_e32 vcc, s84, v188
	s_cbranch_vccz .LBB0_1380
	v_max_f32_e32 v188, v247, v247
	v_max_f32_e32 v189, 0, v188
	v_exp_f32_e64 v188, -v189
	v_max_f32_e32 v2, v2, v2
	v_sub_f32_e32 v152, v152, v189
	v_sub_f32_e32 v153, v153, v189
	v_pk_mul_f32 v[86:87], v[86:87], v[188:189] op_sel_hi:[1,0]
	v_pk_mul_f32 v[84:85], v[84:85], v[188:189] op_sel_hi:[1,0]
	v_pk_mul_f32 v[78:79], v[78:79], v[188:189] op_sel_hi:[1,0]
	v_pk_mul_f32 v[76:77], v[76:77], v[188:189] op_sel_hi:[1,0]
	v_pk_mul_f32 v[30:31], v[30:31], v[188:189] op_sel_hi:[1,0]
	v_pk_mul_f32 v[28:29], v[28:29], v[188:189] op_sel_hi:[1,0]
	v_pk_mul_f32 v[26:27], v[26:27], v[188:189] op_sel_hi:[1,0]
	v_pk_mul_f32 v[24:25], v[24:25], v[188:189] op_sel_hi:[1,0]
	v_pk_mul_f32 v[22:23], v[22:23], v[188:189] op_sel_hi:[1,0]
	v_pk_mul_f32 v[20:21], v[20:21], v[188:189] op_sel_hi:[1,0]
	v_pk_mul_f32 v[18:19], v[18:19], v[188:189] op_sel_hi:[1,0]
	v_pk_mul_f32 v[16:17], v[16:17], v[188:189] op_sel_hi:[1,0]
	v_pk_mul_f32 v[14:15], v[14:15], v[188:189] op_sel_hi:[1,0]
	v_pk_mul_f32 v[12:13], v[12:13], v[188:189] op_sel_hi:[1,0]
	v_pk_mul_f32 v[10:11], v[10:11], v[188:189] op_sel_hi:[1,0]
	v_pk_mul_f32 v[8:9], v[8:9], v[188:189] op_sel_hi:[1,0]
	v_pk_mul_f32 v[6:7], v[6:7], v[188:189] op_sel_hi:[1,0]
	v_pk_mul_f32 v[4:5], v[4:5], v[188:189] op_sel_hi:[1,0]
	v_max_f32_e32 v188, 0, v2
	v_exp_f32_e64 v2, -v188
	v_sub_f32_e32 v154, v154, v189
	v_sub_f32_e32 v155, v155, v189
	v_sub_f32_e32 v148, v148, v189
	v_sub_f32_e32 v149, v149, v189
	v_sub_f32_e32 v150, v150, v189
	v_sub_f32_e32 v151, v151, v189
	v_sub_f32_e32 v144, v144, v189
	v_sub_f32_e32 v145, v145, v189
	v_sub_f32_e32 v146, v146, v189
	v_sub_f32_e32 v147, v147, v189
	v_sub_f32_e32 v140, v140, v189
	v_sub_f32_e32 v141, v141, v189
	v_sub_f32_e32 v142, v142, v189
	v_sub_f32_e32 v143, v143, v189
	v_pk_add_f32 v[212:213], v[212:213], v[188:189]
	v_pk_mul_f32 v[90:91], v[90:91], v[2:3] op_sel_hi:[1,0]
	v_pk_mul_f32 v[88:89], v[88:89], v[2:3] op_sel_hi:[1,0]
	v_pk_mul_f32 v[82:83], v[82:83], v[2:3] op_sel_hi:[1,0]
	v_pk_mul_f32 v[80:81], v[80:81], v[2:3] op_sel_hi:[1,0]
	v_pk_mul_f32 v[74:75], v[74:75], v[2:3] op_sel_hi:[1,0]
	v_pk_mul_f32 v[72:73], v[72:73], v[2:3] op_sel_hi:[1,0]
	v_pk_mul_f32 v[54:55], v[54:55], v[2:3] op_sel_hi:[1,0]
	v_pk_mul_f32 v[52:53], v[52:53], v[2:3] op_sel_hi:[1,0]
	v_pk_mul_f32 v[50:51], v[50:51], v[2:3] op_sel_hi:[1,0]
	v_pk_mul_f32 v[48:49], v[48:49], v[2:3] op_sel_hi:[1,0]
	v_pk_mul_f32 v[46:47], v[46:47], v[2:3] op_sel_hi:[1,0]
	v_pk_mul_f32 v[44:45], v[44:45], v[2:3] op_sel_hi:[1,0]
	v_pk_mul_f32 v[42:43], v[42:43], v[2:3] op_sel_hi:[1,0]
	v_pk_mul_f32 v[40:41], v[40:41], v[2:3] op_sel_hi:[1,0]
	v_pk_mul_f32 v[38:39], v[38:39], v[2:3] op_sel_hi:[1,0]
	v_pk_mul_f32 v[36:37], v[36:37], v[2:3] op_sel_hi:[1,0]
	v_pk_mul_f32 v[34:35], v[34:35], v[2:3] op_sel_hi:[1,0]
	v_pk_mul_f32 v[32:33], v[32:33], v[2:3] op_sel_hi:[1,0]
	v_sub_f32_e32 v136, v136, v188
	v_sub_f32_e32 v137, v137, v188
	v_sub_f32_e32 v138, v138, v188
	v_sub_f32_e32 v139, v139, v188
	v_sub_f32_e32 v132, v132, v188
	v_sub_f32_e32 v133, v133, v188
	v_sub_f32_e32 v134, v134, v188
	v_sub_f32_e32 v135, v135, v188
	v_sub_f32_e32 v128, v128, v188
	v_sub_f32_e32 v129, v129, v188
	v_sub_f32_e32 v130, v130, v188
	v_sub_f32_e32 v131, v131, v188
	v_sub_f32_e32 v124, v124, v188
	v_sub_f32_e32 v125, v125, v188
	v_sub_f32_e32 v126, v126, v188
	v_sub_f32_e32 v127, v127, v188

; #define LAS __attribute__((address_space(3)))
; template <class Epi, class Sched, bool ALIGN_EPI>
; __device__ __forceinline__ void gemm_phase(LAS unsigned char* lds, const bf16_t* Ab, const bf16_t* Bb, int lda, int ldb, int K, const Sched& S, Epi& E) {
;     int tid = threadIdx.x; asm volatile("" : "+v"(tid));
;     const int wid = __builtin_amdgcn_readfirstlane(tid >> 6), lane = tid & 63, wr = wid >> 2, wc = wid & 3, fr = lane & 15, fq = lane >> 4;
;     const int nt = K / BK;
;     unsigned voffA[2], voffB[2]; int aoff, boff;
;     ...
;     PG8_LANEOFFS(tid);
;     const unsigned kstep = (unsigned)(BK * 2);
;     const unsigned hstepA = (unsigned)HALF * lda * 2, hstepB = (unsigned)HALF * ldb * 2;
;     const unsigned ldsw = (unsigned)wid * 1024u;
;     ...
;     Unit cur, nxt; int ui = 0;
;     if (!S.next(0, cur)) return;
;     cur.ui = 0;
;     if constexpr (Epi::HAS_RS) {
;         LAS float* rst = (LAS float*)(lds + LDS_RS);
;         f32x4 pp[RS_MAX_UNITS / 2][4]; bool okk[RS_MAX_UNITS / 2];
; #pragma unroll
;         for (int j = 0; j < RS_MAX_UNITS / 2; ++j) { Unit uu; okk[j] = S.next((tid >> 8) + 2 * j, uu);
;             if (okk[j]) { const f32x4* p = (const f32x4*)(E.ss + (size_t)(uu.pm * 256 + (tid & 255)) * 16); pp[j][0] = p[0]; pp[j][1] = p[1]; pp[j][2] = p[2]; pp[j][3] = p[3]; } }
; #pragma unroll
;         for (int j = 0; j < RS_MAX_UNITS / 2; ++j) if (okk[j]) { const f32x4 a = pp[j][0], b = pp[j][1], c = pp[j][2], d = pp[j][3];
;             const float sm = (((a[0] + a[1]) + (a[2] + a[3])) + ((b[0] + b[1]) + (b[2] + b[3]))) + (((c[0] + c[1]) + (c[2] + c[3])) + ((d[0] + d[1]) + (d[2] + d[3])));
;             rst[((tid >> 8) + 2 * j) * 256 + (tid & 255)] = rsqrtf(sm * Epi::RS_INVN + EPS); }
;         __syncthreads();
;     }
;     f32x4 acc[2][2][4][2];
; #pragma unroll
;     for (int a = 0; a < 2; ++a)
; #pragma unroll
;         for (int b = 0; b < 2; ++b)
; #pragma unroll
;             for (int m = 0; m < 4; ++m)
; #pragma unroll
; __global__ void __launch_bounds__(512, 2) fwd_kernel(Args a) {
;     ...
;         GSYNC();
;         for (int rep = 0; rep < (PROBE == 3 ? 2 : 1); ++rep)
;         { PH XaSched S{G, bid, 4u * 65536u, 65536u}; EpiPV E{(bf16_t*)(ar + AR_OX)};
;           gemm_phase<EpiPV, XaSched, false>(lds, (const bf16_t*)(ar + AR_P), (const bf16_t*)(ws + WS_VXT) + (size_t)l * 1024 * 1024, D, 256, 256, S, E); }
.LBB0_1755:
	s_waitcnt vmcnt(0) lgkmcnt(0)
	v_readlane_b32 s4, v255, 8
	s_mov_b64 s[6:7], s[0:1]
	s_mov_b32 s2, s94
	s_mov_b32 s8, s4
	v_mov_b32_e32 v0, v236
	v_mov_b32_e32 v16, v236
	s_waitcnt lgkmcnt(0)
	s_barrier
	s_cmpk_lt_i32 s8, 0x200
	v_readfirstlane_b32 s4, v16
	v_readlane_b32 s5, v255, 9
	s_cbranch_scc0 .LBB0_1820
	v_bfe_i32 v2, v16, 27, 1
	v_lshlrev_b32_e32 v3, 4, v16
	v_lshrrev_b32_e32 v2, 22, v2
	v_add_u32_e32 v2, v3, v2
	v_and_b32_e32 v2, 0xfffffc00, v2
	v_sub_u32_e32 v2, v3, v2
	s_load_dwordx2 s[6:7], s[6:7], 0x128
	v_lshrrev_b32_e32 v4, 4, v2
	v_bitop3_b32 v2, v4, v2, 32 bitop3:0x6c
	v_ashrrev_i32_e32 v5, 31, v2
	v_ashrrev_i32_e32 v0, 31, v16
	v_lshrrev_b32_e32 v5, 26, v5
	v_lshrrev_b32_e32 v0, 26, v0
	v_add_u32_e32 v5, v2, v5
	s_waitcnt lgkmcnt(0)
	s_add_u32 s5, s6, 0x12800000
	v_add_u32_e32 v0, v16, v0
	v_ashrrev_i32_e32 v6, 6, v5
	v_and_b32_e32 v5, 0xc0, v5
	s_addc_u32 s21, s7, 0
	v_ashrrev_i32_e32 v0, 6, v0
	v_sub_u32_e32 v2, v2, v5
	s_add_u32 s9, s6, s50
	v_lshlrev_b32_e32 v4, 3, v0
	v_lshlrev_b32_e32 v0, 5, v0
	v_ashrrev_i16_sdwa v2, v254, sext(v2) dst_sel:DWORD dst_unused:UNUSED_PAD src0_sel:DWORD src1_sel:BYTE_0
	s_addc_u32 s10, s7, s51
	v_and_b32_e32 v4, -16, v4
	v_and_b32_e32 v0, 32, v0
	v_bfe_i32 v2, v2, 0, 16
	s_add_u32 s22, s9, 0xc00000
	v_add_u32_e32 v4, v6, v4
	v_and_b32_e32 v6, 3, v6
	s_mov_b32 s9, 0x7fffe0
	v_add_lshl_u32 v2, v0, v2, 1
	v_add_u32_e32 v3, 0x2000, v3
	v_lshlrev_b32_e32 v5, 1, v4
	v_lshrrev_b32_e32 v7, 2, v4
	v_and_or_b32 v6, v4, s9, v6
	v_lshl_add_u32 v0, v4, 11, v2
	v_ashrrev_i32_e32 v4, 31, v3
	v_lshrrev_b32_e32 v4, 22, v4
	v_and_b32_e32 v5, 24, v5
	v_and_b32_e32 v7, 4, v7
	v_add_u32_e32 v4, v3, v4
	v_or3_b32 v5, v6, v7, v5
	v_ashrrev_i32_e32 v4, 10, v4
	v_lshl_add_u32 v2, v5, 9, v2
	v_mul_i32_i24_e32 v5, 0x400, v4
	v_sub_u32_e32 v3, v3, v5
	v_lshrrev_b32_e32 v5, 4, v3
	v_bitop3_b32 v3, v5, v3, 32 bitop3:0x6c
	v_ashrrev_i32_e32 v6, 31, v3
	v_lshrrev_b32_e32 v6, 26, v6
	v_lshlrev_b32_e32 v5, 3, v4
	v_add_u32_e32 v6, v3, v6
	v_and_b32_e32 v5, -16, v5
	v_ashrrev_i32_e32 v7, 6, v6
	v_add_u32_e32 v5, v7, v5
	v_and_b32_e32 v7, 3, v7
	s_addc_u32 s24, s10, 0
	v_and_or_b32 v7, v5, s9, v7
	s_ashr_i32 s9, s8, 5
	s_and_b32 s62, s8, 31
	s_ashr_i32 s12, s8, 7
	s_and_b32 s13, s9, 3
	s_lshl_b32 s14, s62, 18
	s_lshl_b32 s15, s12, 23
	s_or_b32 s14, s15, s14
	s_lshl_b32 s15, s13, 8
	s_lshl_b32 s12, s12, 18
	s_lshl_b32 s13, s13, 16
	s_ashr_i32 s10, s4, 6
	s_or_b32 s12, s13, s12
	s_mov_b32 s13, s19
	v_and_b32_e32 v6, 0xc0, v6
	s_ashr_i32 s11, s4, 8
	s_lshl_b32 s25, s10, 10
	s_or_b32 s18, s14, s15
	s_lshl_b64 s[12:13], s[12:13], 1
	v_sub_u32_e32 v3, v3, v6
	s_add_u32 s52, s22, s12
	v_lshlrev_b32_e32 v4, 5, v4
	v_ashrrev_i16_sdwa v3, v254, sext(v3) dst_sel:DWORD dst_unused:UNUSED_PAD src0_sel:DWORD src1_sel:BYTE_0
	v_lshlrev_b32_e32 v6, 1, v5
	v_lshrrev_b32_e32 v8, 2, v5
	s_addc_u32 s53, s24, s13
	s_add_i32 s31, s25, 0
	v_and_b32_e32 v4, 32, v4
	v_bfe_i32 v3, v3, 0, 16
	v_and_b32_e32 v6, 24, v6
	v_and_b32_e32 v8, 4, v8
	s_add_i32 m0, s31, 0x10000
	v_or3_b32 v7, v7, v8, v6
	v_add_lshl_u32 v3, v4, v3, 1
	global_load_lds_dwordx4 v2, s[52:53]
	s_add_i32 m0, s31, 0x12000
	v_lshl_add_u32 v4, v7, 9, v3
	s_add_u32 s12, s52, 0x10000
	global_load_lds_dwordx4 v4, s[52:53]
	s_addc_u32 s13, s53, 0
	s_add_i32 m0, s31, 0x14000
	v_lshl_add_u32 v6, v5, 11, v3
	global_load_lds_dwordx4 v2, s[12:13]
	s_add_i32 m0, s31, 0x16000
	v_mov_b32_e32 v3, v1
	global_load_lds_dwordx4 v4, s[12:13]
	s_lshl_b64 s[12:13], s[18:19], 1
	s_add_u32 s48, s5, s12
	s_addc_u32 s49, s21, s13
	s_add_i32 s33, s31, 0x2000
	s_mov_b32 m0, s31
	s_add_u32 s12, s48, 0x40000
	global_load_lds_dwordx4 v0, s[48:49]
	s_mov_b32 m0, s33
	s_addc_u32 s13, s49, 0
	s_add_i32 s39, s31, 0x4000
	global_load_lds_dwordx4 v6, s[48:49]
	s_mov_b32 m0, s39
	s_add_i32 s44, s31, 0x6000
	global_load_lds_dwordx4 v0, s[12:13]
	s_mov_b32 m0, s44
	v_mov_b32_e32 v5, v1
	global_load_lds_dwordx4 v6, s[12:13]
	v_mov_b32_e32 v7, v1
	v_lshl_add_u64 v[14:15], s[52:53], 0, v[2:3]
	v_lshl_add_u64 v[12:13], s[52:53], 0, v[4:5]
	v_lshl_add_u64 v[10:11], s[48:49], 0, v[0:1]
	s_cmp_lg_u32 s11, 1
	v_lshl_add_u64 v[8:9], s[48:49], 0, v[6:7]
	s_cbranch_scc1 .LBB0_1811
	s_barrier
